# SWA tile loop: 16 of the 32 serial T5-bias LDS lookups given private temporaries and issued in batches of up to 4 ahead of their consumers (on top of v42)
# baseline (speedup 1.0000x reference)
; #define LAS __attribute__((address_space(3)))
; __device__ __forceinline__ void swa_unit(const Ctx& C, const Params& p, int l, int unit) {
;     ...
;             const LAS unsigned char* Kb = lds + (kt - kt_lo) * STILE; const LAS unsigned char* Vb = Kb + 64 * SROW;
;             const int k0 = kt * 64;
;             f32x4 s[2][4];
; #pragma unroll
;             for (int blk = 0; blk < 4; ++blk) {
;                 bf16x8 kf[2];
; #pragma unroll
;                 for (int kk = 0; kk < 2; ++kk) kf[kk] = *(const LAS bf16x8*)(Kb + (blk * 16 + fr) * SROW + (kk * 32 + fq * 8) * 2);
; #pragma unroll
;                 for (int g = 0; g < 2; ++g) { f32x4 a = (f32x4){0.f, 0.f, 0.f, 0.f};
; #pragma unroll
;                     for (int kk = 0; kk < 2; ++kk) a = __builtin_amdgcn_mfma_f32_16x16x32_bf16(kf[kk], qf[g][kk], a, 0, 0, 0);
;                     s[g][blk] = a; }
;             }
;             bf16x8 pf[2][2];
; #pragma unroll
;             for (int g = 0; g < 2; ++g) {
;                 const int qi = q0w + 16 * g + fr;
; #pragma unroll
;                 for (int blk = 0; blk < 4; ++blk) { const int4 t4 = *(const int4*)(p.pos + tok0 + k0 + blk * 16 + fq * 4); const int pkv[4] = {t4.x, t4.y, t4.z, t4.w};
; #pragma unroll
;                     for (int j = 0; j < 4; ++j) { const int key = k0 + blk * 16 + fq * 4 + j; int dd = pq[g] - pkv[j]; dd = dd < 0 ? 0 : (dd > 128 ? 128 : dd);
;                         const float v = s[g][blk][j] * c2 + bth[dd]; const bool ok = (key <= qi) && (qi - key < 128); s[g][blk][j] = ok ? v : -1e30f; } }
.LBB0_276:
	global_load_dwordx4 v[198:201], v[102:103], off
	global_load_dwordx4 v[202:205], v[102:103], off offset:64
	global_load_dwordx4 v[206:209], v[102:103], off offset:128
	global_load_dwordx4 v[210:213], v[102:103], off offset:192
	ds_read_b128 v[50:53], v126
	s_nop 0
	ds_read_b128 v[54:57], v126 offset:64
	v_mov_b32_e32 v129, v66
	v_mov_b32_e32 v108, v0
	v_cmp_le_i32_e32 vcc, v127, v118
	s_waitcnt vmcnt(7) lgkmcnt(1)
	v_mfma_f32_16x16x32_bf16 v[58:61], v[50:53], v[2:5], 0
	v_add_u32_e32 v150, 2, v127
	v_add_u32_e32 v151, 3, v127
	v_add_u32_e32 v152, 17, v127
	s_waitcnt vmcnt(5)
	v_mfma_f32_16x16x32_bf16 v[50:53], v[50:53], v[10:13], 0
	v_add_u32_e32 v153, 18, v127
	v_add_u32_e32 v154, 19, v127
	v_add_u32_e32 v155, 32, v127
	s_waitcnt lgkmcnt(0)
	v_mfma_f32_16x16x32_bf16 v[78:81], v[54:57], v[6:9], v[58:61]
	v_add_u32_e32 v156, 33, v127
	v_add_u32_e32 v157, 34, v127
	v_add_u32_e32 v158, 35, v127
	s_waitcnt vmcnt(4)
	v_mfma_f32_16x16x32_bf16 v[70:73], v[54:57], v[14:17], v[50:53]
	s_nop 2
	ds_read_b128 v[50:53], v126 offset:2304
	ds_read_b128 v[54:57], v126 offset:2368
	v_add_u32_e32 v159, 48, v127
	v_subrev_u32_e32 v128, 64, v109
	s_waitcnt lgkmcnt(1)
	v_mfma_f32_16x16x32_bf16 v[58:61], v[50:53], v[2:5], 0
	v_cmp_gt_i32_e64 s[62:63], s26, v128
	v_add_u32_e32 v160, 49, v127
	v_add_u32_e32 v161, 50, v127
	v_mfma_f32_16x16x32_bf16 v[50:53], v[50:53], v[10:13], 0
	v_add_u32_e32 v162, 51, v127
	s_add_i32 s9, s9, 1
	s_waitcnt lgkmcnt(0)
	v_mfma_f32_16x16x32_bf16 v[82:85], v[54:57], v[6:9], v[58:61]
	v_mfma_f32_16x16x32_bf16 v[66:69], v[54:57], v[14:17], v[50:53]
	s_nop 2
	ds_read_b128 v[50:53], v126 offset:4608
	ds_read_b128 v[58:61], v126 offset:4672
	s_waitcnt lgkmcnt(1)
	v_mfma_f32_16x16x32_bf16 v[54:57], v[50:53], v[2:5], 0
	v_mfma_f32_16x16x32_bf16 v[50:53], v[50:53], v[10:13], 0
	s_waitcnt lgkmcnt(0)
	v_mfma_f32_16x16x32_bf16 v[54:57], v[58:61], v[6:9], v[54:57]
	v_mfma_f32_16x16x32_bf16 v[62:65], v[58:61], v[14:17], v[50:53]
	ds_read_b128 v[58:61], v126 offset:6912
	ds_read_b128 v[74:77], v126 offset:6976
	v_add_u32_e32 v126, 0x4800, v126
	s_waitcnt lgkmcnt(1)
	v_mfma_f32_16x16x32_bf16 v[50:53], v[58:61], v[2:5], 0
	v_mfma_f32_16x16x32_bf16 v[58:61], v[58:61], v[10:13], 0
	s_waitcnt lgkmcnt(0)
	v_mfma_f32_16x16x32_bf16 v[50:53], v[74:77], v[6:9], v[50:53]
	v_mfma_f32_16x16x32_bf16 v[58:61], v[74:77], v[14:17], v[58:61]
	s_waitcnt vmcnt(3)
	v_mov_b32_e32 v74, v198
	v_mov_b32_e32 v75, v199
	v_mov_b32_e32 v76, v200
	v_mov_b32_e32 v77, v201
	v_sub_u32_e32 v0, v114, v74
	v_med3_i32 v0, v0, 0, v180
	v_lshl_add_u32 v0, v0, 2, s8
	ds_read_b32 v0, v0
	v_sub_u32_e32 v74, v115, v74
	v_med3_i32 v74, v74, 0, v180
	v_lshl_add_u32 v74, v74, 2, s8
	ds_read_b32 v74, v74
	s_waitcnt lgkmcnt(1)
	v_fmac_f32_e32 v0, 0x3e38aa3b, v78
	v_add_u32_e32 v78, -16, v109
	v_cmp_gt_i32_e64 s[0:1], s26, v78
	s_and_b64 vcc, vcc, s[0:1]
	v_cndmask_b32_e32 v104, v181, v0, vcc
	v_sub_u32_e32 v214, v114, v75
	v_med3_i32 v214, v214, 0, v180
	v_lshl_add_u32 v214, v214, 2, s8
	ds_read_b32 v214, v214
	v_sub_u32_e32 v215, v114, v76
	v_med3_i32 v215, v215, 0, v180
	v_lshl_add_u32 v215, v215, 2, s8
	ds_read_b32 v215, v215
	v_sub_u32_e32 v216, v114, v77
	v_med3_i32 v216, v216, 0, v180
	v_lshl_add_u32 v216, v216, 2, s8
	ds_read_b32 v216, v216
	v_subrev_u32_e32 v78, 17, v109
	v_cmp_lt_i32_e64 s[0:1], v127, v118
	v_cmp_gt_i32_e64 s[36:37], s26, v78
	s_and_b64 s[0:1], s[0:1], s[36:37]
	s_waitcnt lgkmcnt(0)
	v_fmac_f32_e32 v214, 0x3e38aa3b, v79
	v_cndmask_b32_e64 v105, v181, v214, s[0:1]
	v_subrev_u32_e32 v78, 18, v109
	v_cmp_le_i32_e64 s[0:1], v150, v118
	v_cmp_gt_i32_e64 s[38:39], s26, v78
	s_and_b64 s[0:1], s[0:1], s[38:39]
	s_waitcnt lgkmcnt(0)
	v_fmac_f32_e32 v215, 0x3e38aa3b, v80
	v_cndmask_b32_e64 v106, v181, v215, s[0:1]
	v_subrev_u32_e32 v78, 19, v109
	v_cmp_gt_i32_e64 s[40:41], s26, v78
	v_cmp_le_i32_e64 s[0:1], v151, v118
	s_and_b64 s[0:1], s[0:1], s[40:41]
	s_waitcnt lgkmcnt(0)
	v_fmac_f32_e32 v216, 0x3e38aa3b, v81
	s_waitcnt vmcnt(2)
	v_mov_b32_e32 v78, v202
	v_mov_b32_e32 v79, v203
	v_mov_b32_e32 v80, v204
	v_mov_b32_e32 v81, v205
	v_cndmask_b32_e64 v107, v181, v216, s[0:1]
	v_add_u32_e32 v0, 16, v127
	v_cmp_le_i32_e64 s[0:1], v0, v118
	v_subrev_u32_e32 v0, 32, v109
	v_cmp_gt_i32_e64 s[42:43], s26, v0
	s_and_b64 s[0:1], s[0:1], s[42:43]
	v_fmac_f32_e32 v74, 0x3e38aa3b, v70
	v_max_f32_e32 v130, v106, v107
	v_sub_u32_e32 v86, v114, v78
	v_med3_i32 v86, v86, 0, v180
	v_lshl_add_u32 v86, v86, 2, s8
	v_sub_u32_e32 v0, v114, v79
	ds_read_b32 v86, v86
	v_med3_i32 v0, v0, 0, v180
	v_lshl_add_u32 v0, v0, 2, s8
	ds_read_b32 v0, v0
	s_waitcnt lgkmcnt(1)
	v_fmac_f32_e32 v86, 0x3e38aa3b, v82
	v_subrev_u32_e32 v82, 33, v109
	v_cndmask_b32_e64 v110, v181, v86, s[0:1]
	v_cmp_le_i32_e64 s[0:1], v152, v118
	v_cmp_gt_i32_e64 s[44:45], s26, v82
	s_waitcnt lgkmcnt(0)
	v_fmac_f32_e32 v0, 0x3e38aa3b, v83
	s_and_b64 s[0:1], s[0:1], s[44:45]
	v_cndmask_b32_e64 v111, v181, v0, s[0:1]
	v_sub_u32_e32 v217, v114, v80
	v_med3_i32 v217, v217, 0, v180
	v_lshl_add_u32 v217, v217, 2, s8
	ds_read_b32 v217, v217
	v_sub_u32_e32 v218, v114, v81
	v_med3_i32 v218, v218, 0, v180
	v_lshl_add_u32 v218, v218, 2, s8
	ds_read_b32 v218, v218
	v_subrev_u32_e32 v82, 34, v109
	v_cmp_le_i32_e64 s[0:1], v153, v118
	v_cmp_gt_i32_e64 s[46:47], s26, v82
	s_and_b64 s[0:1], s[0:1], s[46:47]
	s_waitcnt lgkmcnt(0)
	v_fmac_f32_e32 v217, 0x3e38aa3b, v84
	v_cndmask_b32_e64 v112, v181, v217, s[0:1]
	v_subrev_u32_e32 v82, 35, v109
	v_cmp_gt_i32_e64 s[48:49], s26, v82
	s_waitcnt vmcnt(0)
	v_mov_b32_e32 v86, v210
	v_mov_b32_e32 v87, v211
	v_mov_b32_e32 v88, v212
	v_mov_b32_e32 v89, v213
	v_cmp_le_i32_e64 s[0:1], v154, v118
	s_waitcnt lgkmcnt(0)
; __device__ __forceinline__ unsigned pkhw(float lo, float hi) { f32x2q v = {lo, hi}; bf16x2q b = __builtin_convertvector(v, bf16x2q); return __builtin_bit_cast(unsigned, b); }
; __device__ __forceinline__ void swa_unit(const Ctx& C, const Params& p, int l, int unit) {
;     ...
;                 for (int blk = 0; blk < 4; ++blk) { const int4 t4 = *(const int4*)(p.pos + tok0 + k0 + blk * 16 + fq * 4); const int pkv[4] = {t4.x, t4.y, t4.z, t4.w};
; #pragma unroll
;                     for (int j = 0; j < 4; ++j) { const int key = k0 + blk * 16 + fq * 4 + j; int dd = pq[g] - pkv[j]; dd = dd < 0 ? 0 : (dd > 128 ? 128 : dd);
;                         const float v = s[g][blk][j] * c2 + bth[dd]; const bool ok = (key <= qi) && (qi - key < 128); s[g][blk][j] = ok ? v : -1e30f; } }
;                 float mx = fmaxf(fmaxf(s[g][0][0], s[g][0][1]), fmaxf(s[g][0][2], s[g][0][3]));
; #pragma unroll
;                 for (int blk = 1; blk < 4; ++blk) mx = fmaxf(mx, fmaxf(fmaxf(s[g][blk][0], s[g][blk][1]), fmaxf(s[g][blk][2], s[g][blk][3])));
;                 mx = rowmax4(mx);
;                 const float mn = fmaxf(m[g], mx), alpha = __builtin_amdgcn_exp2f(m[g] - mn); m[g] = mn;
;                 f32x2 ps2 = (f32x2){0.f, 0.f}; const f32x2 mnv = (f32x2){mn, mn};
; #pragma unroll
;                 for (int blk = 0; blk < 4; ++blk)
; #pragma unroll
;                     for (int jp = 0; jp < 2; ++jp) { f32x2 x = (f32x2){s[g][blk][2 * jp], s[g][blk][2 * jp + 1]}; x = x - mnv;
;                         f32x2 pv; pv.x = __builtin_amdgcn_exp2f(x.x); pv.y = __builtin_amdgcn_exp2f(x.y); ps2 = ps2 + pv; s[g][blk][2 * jp] = pv.x; s[g][blk][2 * jp + 1] = pv.y; }
;                 const float ps = ps2.x + ps2.y;
;                 lsum[g] = lsum[g] * alpha + ps;
; #pragma unroll
;                 for (int d = 0; d < 4; ++d) o[g][d] = o[g][d] * alpha;
; #pragma unroll
;                 for (int hf = 0; hf < 2; ++hf) { v4u pw; pw.x = pkhw(s[g][2 * hf][0], s[g][2 * hf][1]); pw.y = pkhw(s[g][2 * hf][2], s[g][2 * hf][3]); pw.z = pkhw(s[g][2 * hf + 1][0], s[g][2 * hf + 1][1]); pw.w = pkhw(s[g][2 * hf + 1][2], s[g][2 * hf + 1][3]);
	v_fmac_f32_e32 v218, 0x3e38aa3b, v85
	v_mov_b32_e32 v82, v206
	v_mov_b32_e32 v83, v207
	v_mov_b32_e32 v84, v208
	v_mov_b32_e32 v85, v209
	s_and_b64 s[0:1], s[0:1], s[48:49]
	v_cndmask_b32_e64 v113, v181, v218, s[0:1]
	v_cmp_le_i32_e64 s[0:1], v155, v118
	v_max_f32_e32 v131, v112, v113
	v_max3_f32 v131, v110, v111, v131
	v_sub_u32_e32 v219, v114, v82
	v_med3_i32 v219, v219, 0, v180
	v_lshl_add_u32 v219, v219, 2, s8
	ds_read_b32 v219, v219
	v_sub_u32_e32 v220, v114, v83
	v_med3_i32 v220, v220, 0, v180
	v_lshl_add_u32 v220, v220, 2, s8
	ds_read_b32 v220, v220
	v_sub_u32_e32 v221, v114, v84
	v_med3_i32 v221, v221, 0, v180
	v_lshl_add_u32 v221, v221, 2, s8
	ds_read_b32 v221, v221
	v_sub_u32_e32 v214, v114, v85
	v_med3_i32 v214, v214, 0, v180
	v_lshl_add_u32 v214, v214, 2, s8
	ds_read_b32 v214, v214
	s_waitcnt lgkmcnt(0)
	v_fmac_f32_e32 v219, 0x3e38aa3b, v54
	v_subrev_u32_e32 v54, 48, v109
	v_cmp_gt_i32_e64 s[50:51], s26, v54
	s_and_b64 s[0:1], s[0:1], s[50:51]
	v_cndmask_b32_e64 v54, v181, v219, s[0:1]
	v_cmp_le_i32_e64 s[0:1], v156, v118
	s_waitcnt lgkmcnt(0)
	v_fmac_f32_e32 v220, 0x3e38aa3b, v55
	v_subrev_u32_e32 v55, 49, v109
	v_cmp_gt_i32_e64 s[52:53], s26, v55
	s_and_b64 s[0:1], s[0:1], s[52:53]
	v_cndmask_b32_e64 v55, v181, v220, s[0:1]
	v_cmp_le_i32_e64 s[0:1], v157, v118
	s_waitcnt lgkmcnt(0)
	v_fmac_f32_e32 v221, 0x3e38aa3b, v56
	v_subrev_u32_e32 v56, 50, v109
	v_cmp_gt_i32_e64 s[54:55], s26, v56
	s_and_b64 s[0:1], s[0:1], s[54:55]
	v_cndmask_b32_e64 v56, v181, v221, s[0:1]
	v_cmp_le_i32_e64 s[0:1], v158, v118
	s_waitcnt lgkmcnt(0)
	v_fmac_f32_e32 v214, 0x3e38aa3b, v57
	v_subrev_u32_e32 v57, 51, v109
	v_cmp_gt_i32_e64 s[56:57], s26, v57
	s_and_b64 s[0:1], s[0:1], s[56:57]
	v_cndmask_b32_e64 v57, v181, v214, s[0:1]
	v_sub_u32_e32 v215, v114, v86
	v_med3_i32 v215, v215, 0, v180
	v_lshl_add_u32 v215, v215, 2, s8
	ds_read_b32 v215, v215
	v_sub_u32_e32 v216, v114, v87
	v_med3_i32 v216, v216, 0, v180
	v_lshl_add_u32 v216, v216, 2, s8
	ds_read_b32 v216, v216
	v_sub_u32_e32 v217, v114, v88
	v_med3_i32 v217, v217, 0, v180
	v_lshl_add_u32 v217, v217, 2, s8
	ds_read_b32 v217, v217
	v_sub_u32_e32 v218, v114, v89
	v_med3_i32 v218, v218, 0, v180
	v_lshl_add_u32 v218, v218, 2, s8
	ds_read_b32 v218, v218
	v_cmp_le_i32_e64 s[0:1], v159, v118
	s_and_b64 s[0:1], s[0:1], s[62:63]
	s_waitcnt lgkmcnt(0)
	v_fmac_f32_e32 v215, 0x3e38aa3b, v50
	v_cndmask_b32_e64 v50, v181, v215, s[0:1]
	v_cmp_le_i32_e64 s[0:1], v160, v118
	s_waitcnt lgkmcnt(0)
	v_fmac_f32_e32 v216, 0x3e38aa3b, v51
	v_add_u32_e32 v51, 0xffffffbf, v109
	v_cmp_gt_i32_e64 s[62:63], s26, v51
	s_and_b64 s[0:1], s[0:1], s[62:63]
	v_cndmask_b32_e64 v51, v181, v216, s[0:1]
	v_cmp_le_i32_e64 s[0:1], v161, v118
	s_waitcnt lgkmcnt(0)
	v_fmac_f32_e32 v217, 0x3e38aa3b, v52
	v_add_u32_e32 v52, 0xffffffbe, v109
	v_cmp_gt_i32_e64 s[62:63], s26, v52
	s_and_b64 s[0:1], s[0:1], s[62:63]
	v_cndmask_b32_e64 v52, v181, v217, s[0:1]
	v_cmp_le_i32_e64 s[0:1], v162, v118
	s_waitcnt lgkmcnt(0)
	v_fmac_f32_e32 v218, 0x3e38aa3b, v53
	v_add_u32_e32 v53, 0xffffffbd, v109
	v_cmp_gt_i32_e64 s[62:63], s26, v53
	s_and_b64 s[0:1], s[0:1], s[62:63]
	v_cndmask_b32_e64 v53, v181, v218, s[0:1]
	v_cmp_le_i32_e64 s[0:1], v127, v119
	v_cmp_gt_i32_e64 s[62:63], s26, v109
	s_and_b64 s[0:1], s[0:1], s[62:63]
	v_cndmask_b32_e64 v70, v181, v74, s[0:1]
	v_sub_u32_e32 v219, v115, v75
	v_med3_i32 v219, v219, 0, v180
	v_lshl_add_u32 v219, v219, 2, s8
	ds_read_b32 v219, v219
	v_sub_u32_e32 v220, v115, v76
	v_med3_i32 v220, v220, 0, v180
	v_lshl_add_u32 v220, v220, 2, s8
	ds_read_b32 v220, v220
	v_sub_u32_e32 v221, v115, v77
	v_med3_i32 v221, v221, 0, v180
	v_lshl_add_u32 v221, v221, 2, s8
	ds_read_b32 v221, v221
	v_cmp_lt_i32_e64 s[0:1], v127, v119
	v_max_f32_e32 v0, v104, v105
	v_max3_f32 v0, v0, v130, v131
	v_max_f32_e32 v130, v56, v57
	s_waitcnt lgkmcnt(0)
	v_fmac_f32_e32 v219, 0x3e38aa3b, v71
	v_add_u32_e32 v71, -1, v109
	v_cmp_gt_i32_e64 s[62:63], s26, v71
	s_and_b64 s[0:1], s[0:1], s[62:63]
	v_cndmask_b32_e64 v71, v181, v219, s[0:1]
	v_cmp_le_i32_e64 s[0:1], v150, v119
	v_max_f32_e32 v131, v52, v53
	v_max3_f32 v130, v54, v55, v130
	v_max3_f32 v131, v50, v51, v131
	s_waitcnt lgkmcnt(0)
	v_fmac_f32_e32 v220, 0x3e38aa3b, v72
	v_add_u32_e32 v72, -2, v109
	v_cmp_gt_i32_e64 s[62:63], s26, v72
	s_and_b64 s[0:1], s[0:1], s[62:63]
	v_cndmask_b32_e64 v72, v181, v220, s[0:1]
	v_cmp_le_i32_e64 s[0:1], v151, v119
	v_max3_f32 v0, v0, v130, v131
	v_mov_b32_e32 v130, v0
	s_nop 1
	v_permlane16_swap_b32_e32 v0, v130
	s_waitcnt lgkmcnt(0)
	v_fmac_f32_e32 v221, 0x3e38aa3b, v73
	v_add_u32_e32 v73, -3, v109
	v_cmp_gt_i32_e64 s[62:63], s26, v73
	s_and_b64 s[0:1], s[0:1], s[62:63]
	v_cndmask_b32_e64 v73, v181, v221, s[0:1]
	v_sub_u32_e32 v74, v115, v78
	v_med3_i32 v74, v74, 0, v180
	v_lshl_add_u32 v74, v74, 2, s8
	ds_read_b32 v74, v74
	v_max_f32_e32 v130, v130, v130
	v_max_f32_e32 v0, v0, v0
	v_max_f32_e32 v0, v0, v130
	v_mov_b32_e32 v130, v0
	s_waitcnt lgkmcnt(0)
	v_fmac_f32_e32 v74, 0x3e38aa3b, v66
	v_sub_u32_e32 v66, v115, v79
	v_med3_i32 v66, v66, 0, v180
	v_lshl_add_u32 v66, v66, 2, s8
	ds_read_b32 v66, v66
	v_cndmask_b32_e32 v74, v181, v74, vcc
	v_cmp_le_i32_e32 vcc, v152, v119
	s_and_b64 vcc, vcc, s[36:37]
	v_permlane32_swap_b32_e32 v0, v130
	s_waitcnt lgkmcnt(0)
	v_fmac_f32_e32 v66, 0x3e38aa3b, v67
	v_cndmask_b32_e32 v75, v181, v66, vcc
	v_sub_u32_e32 v66, v115, v80
	v_med3_i32 v66, v66, 0, v180
	v_lshl_add_u32 v66, v66, 2, s8
	ds_read_b32 v66, v66
	v_cmp_le_i32_e32 vcc, v153, v119
	s_and_b64 vcc, vcc, s[38:39]
	v_max_f32_e32 v67, v72, v73
	v_max3_f32 v0, v108, v0, v130
	s_waitcnt lgkmcnt(0)
; __device__ __forceinline__ void swa_unit(const Ctx& C, const Params& p, int l, int unit) {
;     ...
;                 for (int blk = 0; blk < 4; ++blk) { const int4 t4 = *(const int4*)(p.pos + tok0 + k0 + blk * 16 + fq * 4); const int pkv[4] = {t4.x, t4.y, t4.z, t4.w};
; #pragma unroll
;                     for (int j = 0; j < 4; ++j) { const int key = k0 + blk * 16 + fq * 4 + j; int dd = pq[g] - pkv[j]; dd = dd < 0 ? 0 : (dd > 128 ? 128 : dd);
;                         const float v = s[g][blk][j] * c2 + bth[dd]; const bool ok = (key <= qi) && (qi - key < 128); s[g][blk][j] = ok ? v : -1e30f; } }
;                 float mx = fmaxf(fmaxf(s[g][0][0], s[g][0][1]), fmaxf(s[g][0][2], s[g][0][3]));
; #pragma unroll
;                 for (int blk = 1; blk < 4; ++blk) mx = fmaxf(mx, fmaxf(fmaxf(s[g][blk][0], s[g][blk][1]), fmaxf(s[g][blk][2], s[g][blk][3])));
;                 mx = rowmax4(mx);
;                 const float mn = fmaxf(m[g], mx), alpha = __builtin_amdgcn_exp2f(m[g] - mn); m[g] = mn;
;                 f32x2 ps2 = (f32x2){0.f, 0.f}; const f32x2 mnv = (f32x2){mn, mn};
; #pragma unroll
;                 for (int blk = 0; blk < 4; ++blk)
; #pragma unroll
;                     for (int jp = 0; jp < 2; ++jp) { f32x2 x = (f32x2){s[g][blk][2 * jp], s[g][blk][2 * jp + 1]}; x = x - mnv;
;                         f32x2 pv; pv.x = __builtin_amdgcn_exp2f(x.x); pv.y = __builtin_amdgcn_exp2f(x.y); ps2 = ps2 + pv; s[g][blk][2 * jp] = pv.x; s[g][blk][2 * jp + 1] = pv.y; }
	v_fmac_f32_e32 v66, 0x3e38aa3b, v68
	v_cndmask_b32_e32 v68, v181, v66, vcc
	v_sub_u32_e32 v66, v115, v81
	v_med3_i32 v66, v66, 0, v180
	v_lshl_add_u32 v66, v66, 2, s8
	ds_read_b32 v66, v66
	v_cmp_le_i32_e32 vcc, v154, v119
	s_and_b64 vcc, vcc, s[40:41]
	v_pk_add_f32 v[104:105], v[104:105], v[0:1] op_sel_hi:[1,0] neg_lo:[0,1] neg_hi:[0,1]
	v_pk_add_f32 v[106:107], v[106:107], v[0:1] op_sel_hi:[1,0] neg_lo:[0,1] neg_hi:[0,1]
	s_waitcnt lgkmcnt(0)
	v_fmac_f32_e32 v66, 0x3e38aa3b, v69
	v_cndmask_b32_e32 v69, v181, v66, vcc
	v_sub_u32_e32 v66, v115, v82
	v_med3_i32 v66, v66, 0, v180
	v_lshl_add_u32 v66, v66, 2, s8
	ds_read_b32 v66, v66
	v_cmp_le_i32_e32 vcc, v155, v119
	s_and_b64 vcc, vcc, s[42:43]
	v_max_f32_e32 v76, v68, v69
	v_max3_f32 v76, v74, v75, v76
	s_waitcnt lgkmcnt(0)
	v_fmac_f32_e32 v66, 0x3e38aa3b, v62
	v_cndmask_b32_e32 v62, v181, v66, vcc
	v_sub_u32_e32 v66, v115, v83
	v_med3_i32 v66, v66, 0, v180
	v_lshl_add_u32 v66, v66, 2, s8
	ds_read_b32 v66, v66
	v_cmp_le_i32_e32 vcc, v156, v119
	s_and_b64 vcc, vcc, s[44:45]
	v_exp_f32_e32 v130, v104
	v_exp_f32_e32 v131, v105
	s_waitcnt lgkmcnt(0)
	v_fmac_f32_e32 v66, 0x3e38aa3b, v63
	v_cndmask_b32_e32 v63, v181, v66, vcc
	v_sub_u32_e32 v66, v115, v84
	v_med3_i32 v66, v66, 0, v180
	v_lshl_add_u32 v66, v66, 2, s8
	ds_read_b32 v66, v66
	v_cmp_le_i32_e32 vcc, v157, v119
	s_and_b64 vcc, vcc, s[46:47]
	v_exp_f32_e32 v106, v106
	v_exp_f32_e32 v107, v107
	s_waitcnt lgkmcnt(0)
	v_fmac_f32_e32 v66, 0x3e38aa3b, v64
	v_cndmask_b32_e32 v64, v181, v66, vcc
	v_sub_u32_e32 v66, v115, v85
	v_med3_i32 v66, v66, 0, v180
	v_lshl_add_u32 v66, v66, 2, s8
	ds_read_b32 v66, v66
	v_cmp_le_i32_e32 vcc, v158, v119
	s_and_b64 vcc, vcc, s[48:49]
	v_pk_add_f32 v[110:111], v[110:111], v[0:1] op_sel_hi:[1,0] neg_lo:[0,1] neg_hi:[0,1]
	v_pk_add_f32 v[112:113], v[112:113], v[0:1] op_sel_hi:[1,0] neg_lo:[0,1] neg_hi:[0,1]
	s_waitcnt lgkmcnt(0)
	v_fmac_f32_e32 v66, 0x3e38aa3b, v65
	v_cndmask_b32_e32 v65, v181, v66, vcc
	v_sub_u32_e32 v66, v115, v86
	v_med3_i32 v66, v66, 0, v180
	v_lshl_add_u32 v66, v66, 2, s8
	ds_read_b32 v66, v66
	v_cmp_le_i32_e32 vcc, v159, v119
	s_and_b64 vcc, vcc, s[50:51]
	v_exp_f32_e32 v110, v110
	v_exp_f32_e32 v111, v111
	s_waitcnt lgkmcnt(0)
	v_fmac_f32_e32 v66, 0x3e38aa3b, v58
	v_cndmask_b32_e32 v58, v181, v66, vcc
	v_sub_u32_e32 v66, v115, v87
	v_med3_i32 v66, v66, 0, v180
	v_lshl_add_u32 v66, v66, 2, s8
	ds_read_b32 v66, v66
	v_cmp_le_i32_e32 vcc, v160, v119
	s_and_b64 vcc, vcc, s[52:53]
	v_exp_f32_e32 v112, v112
	v_exp_f32_e32 v113, v113
	s_waitcnt lgkmcnt(0)
	v_fmac_f32_e32 v66, 0x3e38aa3b, v59
	v_cndmask_b32_e32 v59, v181, v66, vcc
	v_sub_u32_e32 v66, v115, v88
	v_med3_i32 v66, v66, 0, v180
	v_lshl_add_u32 v66, v66, 2, s8
	ds_read_b32 v66, v66
	v_cmp_le_i32_e32 vcc, v161, v119
	s_and_b64 vcc, vcc, s[54:55]
	v_pk_add_f32 v[54:55], v[54:55], v[0:1] op_sel_hi:[1,0] neg_lo:[0,1] neg_hi:[0,1]
	v_pk_add_f32 v[104:105], v[130:131], 0 op_sel_hi:[1,0]
	s_waitcnt lgkmcnt(0)
	v_fmac_f32_e32 v66, 0x3e38aa3b, v60
	v_cndmask_b32_e32 v60, v181, v66, vcc
	v_sub_u32_e32 v66, v115, v89
	v_med3_i32 v66, v66, 0, v180
	v_lshl_add_u32 v66, v66, 2, s8
	ds_read_b32 v66, v66
	v_cmp_le_i32_e32 vcc, v162, v119
	s_and_b64 vcc, vcc, s[56:57]
	v_exp_f32_e32 v132, v54
	v_exp_f32_e32 v133, v55
	s_waitcnt lgkmcnt(0)
; #define LAS __attribute__((address_space(3)))
; __device__ __forceinline__ unsigned pkhw(float lo, float hi) { f32x2q v = {lo, hi}; bf16x2q b = __builtin_convertvector(v, bf16x2q); return __builtin_bit_cast(unsigned, b); }
; __device__ __forceinline__ void swa_unit(const Ctx& C, const Params& p, int l, int unit) {
;     ...
;                 float mx = fmaxf(fmaxf(s[g][0][0], s[g][0][1]), fmaxf(s[g][0][2], s[g][0][3]));
; #pragma unroll
;                 for (int blk = 1; blk < 4; ++blk) mx = fmaxf(mx, fmaxf(fmaxf(s[g][blk][0], s[g][blk][1]), fmaxf(s[g][blk][2], s[g][blk][3])));
;                 mx = rowmax4(mx);
;                 const float mn = fmaxf(m[g], mx), alpha = __builtin_amdgcn_exp2f(m[g] - mn); m[g] = mn;
;                 f32x2 ps2 = (f32x2){0.f, 0.f}; const f32x2 mnv = (f32x2){mn, mn};
; #pragma unroll
;                 for (int blk = 0; blk < 4; ++blk)
; #pragma unroll
;                     for (int jp = 0; jp < 2; ++jp) { f32x2 x = (f32x2){s[g][blk][2 * jp], s[g][blk][2 * jp + 1]}; x = x - mnv;
;                         f32x2 pv; pv.x = __builtin_amdgcn_exp2f(x.x); pv.y = __builtin_amdgcn_exp2f(x.y); ps2 = ps2 + pv; s[g][blk][2 * jp] = pv.x; s[g][blk][2 * jp + 1] = pv.y; }
;                 const float ps = ps2.x + ps2.y;
;                 lsum[g] = lsum[g] * alpha + ps;
; #pragma unroll
;                 for (int d = 0; d < 4; ++d) o[g][d] = o[g][d] * alpha;
; #pragma unroll
;                 for (int hf = 0; hf < 2; ++hf) { v4u pw; pw.x = pkhw(s[g][2 * hf][0], s[g][2 * hf][1]); pw.y = pkhw(s[g][2 * hf][2], s[g][2 * hf][3]); pw.z = pkhw(s[g][2 * hf + 1][0], s[g][2 * hf + 1][1]); pw.w = pkhw(s[g][2 * hf + 1][2], s[g][2 * hf + 1][3]);
;                     pf[g][hf] = __builtin_bit_cast(bf16x8, pw); }
;             }
; #pragma unroll
;             for (int hf = 0; hf < 2; ++hf)
; #pragma unroll
;                 for (int d = 0; d < 4; ++d) {
;                     const LAS unsigned char* vp = Vb + (d * 16 + fr) * SROW + (hf * 32 + fq * 4) * 2;
;                     const v2u lo = *(const LAS v2u*)vp, hi = *(const LAS v2u*)(vp + 32);
;                     const v4u vw = (v4u){lo.x, lo.y, hi.x, hi.y}; const bf16x8 vf = __builtin_bit_cast(bf16x8, vw);
; #pragma unroll
;                     for (int g = 0; g < 2; ++g) o[g][d] = __builtin_amdgcn_mfma_f32_16x16x32_bf16(vf, pf[g][hf], o[g][d], 0, 0, 0);
;                 }
	v_fmac_f32_e32 v66, 0x3e38aa3b, v61
	v_cndmask_b32_e32 v61, v181, v66, vcc
	v_max_f32_e32 v66, v70, v71
	v_max3_f32 v66, v66, v67, v76
	v_max_f32_e32 v67, v64, v65
	v_max_f32_e32 v76, v60, v61
	v_max3_f32 v67, v62, v63, v67
	v_max3_f32 v76, v58, v59, v76
	v_max3_f32 v66, v66, v67, v76
	v_mov_b32_e32 v67, v66
	s_nop 1
	v_permlane16_swap_b32_e32 v66, v67
	v_max_f32_e32 v67, v67, v67
	v_max_f32_e32 v66, v66, v66
	v_max_f32_e32 v66, v66, v67
	v_mov_b32_e32 v67, v66
	s_nop 1
	v_permlane32_swap_b32_e32 v66, v67
	v_max3_f32 v66, v129, v66, v67
	v_sub_f32_e32 v67, v129, v66
	v_pk_add_f32 v[70:71], v[70:71], v[66:67] op_sel_hi:[1,0] neg_lo:[0,1] neg_hi:[0,1]
	v_pk_add_f32 v[72:73], v[72:73], v[66:67] op_sel_hi:[1,0] neg_lo:[0,1] neg_hi:[0,1]
	v_exp_f32_e32 v70, v70
	v_exp_f32_e32 v71, v71
	v_exp_f32_e32 v72, v72
	v_exp_f32_e32 v73, v73
	v_pk_add_f32 v[74:75], v[74:75], v[66:67] op_sel_hi:[1,0] neg_lo:[0,1] neg_hi:[0,1]
	v_pk_add_f32 v[68:69], v[68:69], v[66:67] op_sel_hi:[1,0] neg_lo:[0,1] neg_hi:[0,1]
	v_exp_f32_e32 v74, v74
	v_exp_f32_e32 v75, v75
	v_exp_f32_e32 v68, v68
	v_exp_f32_e32 v69, v69
	v_pk_add_f32 v[62:63], v[62:63], v[66:67] op_sel_hi:[1,0] neg_lo:[0,1] neg_hi:[0,1]
	v_pk_add_f32 v[76:77], v[70:71], 0 op_sel_hi:[1,0]
	v_exp_f32_e32 v78, v62
	v_exp_f32_e32 v79, v63
	v_pk_add_f32 v[76:77], v[72:73], v[76:77]
	v_pk_add_f32 v[56:57], v[56:57], v[0:1] op_sel_hi:[1,0] neg_lo:[0,1] neg_hi:[0,1]
	v_pk_add_f32 v[76:77], v[74:75], v[76:77]
	v_pk_add_f32 v[64:65], v[64:65], v[66:67] op_sel_hi:[1,0] neg_lo:[0,1] neg_hi:[0,1]
	v_pk_add_f32 v[76:77], v[68:69], v[76:77]
	v_pk_add_f32 v[104:105], v[106:107], v[104:105]
	v_exp_f32_e32 v164, v56
	v_exp_f32_e32 v165, v57
	v_pk_add_f32 v[50:51], v[50:51], v[0:1] op_sel_hi:[1,0] neg_lo:[0,1] neg_hi:[0,1]
	v_pk_add_f32 v[62:63], v[78:79], v[76:77]
	v_exp_f32_e32 v76, v64
	v_exp_f32_e32 v77, v65
	v_pk_add_f32 v[58:59], v[58:59], v[66:67] op_sel_hi:[1,0] neg_lo:[0,1] neg_hi:[0,1]
	v_pk_add_f32 v[104:105], v[110:111], v[104:105]
	v_exp_f32_e32 v166, v50
	v_exp_f32_e32 v167, v51
	v_pk_add_f32 v[52:53], v[52:53], v[0:1] op_sel_hi:[1,0] neg_lo:[0,1] neg_hi:[0,1]
	v_exp_f32_e32 v80, v58
	v_exp_f32_e32 v81, v59
	v_pk_add_f32 v[60:61], v[60:61], v[66:67] op_sel_hi:[1,0] neg_lo:[0,1] neg_hi:[0,1]
	v_sub_f32_e32 v108, v108, v0
	v_pk_add_f32 v[104:105], v[112:113], v[104:105]
	v_exp_f32_e32 v168, v52
	v_exp_f32_e32 v169, v53
	v_exp_f32_e32 v82, v60
	v_exp_f32_e32 v83, v61
	v_exp_f32_e32 v108, v108
	v_pk_add_f32 v[54:55], v[132:133], v[104:105]
	v_exp_f32_e32 v109, v67
	v_pk_add_f32 v[54:55], v[164:165], v[54:55]
	v_pk_add_f32 v[62:63], v[76:77], v[62:63]
	v_pk_add_f32 v[50:51], v[166:167], v[54:55]
	v_pk_add_f32 v[58:59], v[80:81], v[62:63]
	v_pk_add_f32 v[104:105], v[168:169], v[50:51]
	v_pk_add_f32 v[62:63], v[82:83], v[58:59]
	v_pk_mul_f32 v[58:59], v[46:47], v[108:109] op_sel_hi:[1,0]
	v_mov_b32_e32 v46, v104
	v_mov_b32_e32 v47, v62
	v_mov_b32_e32 v62, v105
	v_pk_add_f32 v[46:47], v[46:47], v[62:63]
	v_mov_b32_e32 v84, v109
	v_pk_mul_f32 v[60:61], v[48:49], v[108:109] op_sel_hi:[1,0]
	v_pk_fma_f32 v[100:101], v[100:101], v[108:109], v[46:47]
	v_pk_mul_f32 v[48:49], v[28:29], v[84:85] op_sel_hi:[1,0]
	v_pk_mul_f32 v[46:47], v[26:27], v[84:85] op_sel_hi:[1,0]
	v_cvt_pk_bf16_f32 v26, v70, v71
	v_cvt_pk_bf16_f32 v29, v68, v69
	ds_read2_b64 v[68:71], v125 offset1:4
	v_cvt_pk_bf16_f32 v54, v130, v131
	v_cvt_pk_bf16_f32 v55, v106, v107
	v_cvt_pk_bf16_f32 v56, v110, v111
	v_cvt_pk_bf16_f32 v57, v112, v113
	v_pk_mul_f32 v[64:65], v[32:33], v[84:85] op_sel_hi:[1,0]
	v_pk_mul_f32 v[62:63], v[30:31], v[84:85] op_sel_hi:[1,0]
	v_cvt_pk_bf16_f32 v27, v72, v73
	v_cvt_pk_bf16_f32 v28, v74, v75
	v_add_u32_e32 v67, 0x800, v125
	s_waitcnt lgkmcnt(0)
	v_mfma_f32_16x16x32_bf16 v[58:61], v[68:71], v[54:57], v[58:61]
	v_mul_f32_e64 v44, v44, v108
	v_mul_f32_e64 v45, v45, v108
	v_pk_mul_f32 v[42:43], v[42:43], v[108:109] op_sel_hi:[1,0]
	v_pk_mul_f32 v[30:31], v[22:23], v[84:85] op_sel_hi:[1,0]
	v_mfma_f32_16x16x32_bf16 v[62:65], v[68:71], v[26:29], v[62:65]
	ds_read2_b64 v[68:71], v67 offset0:32 offset1:36
	v_pk_mul_f32 v[22:23], v[18:19], v[84:85] op_sel_hi:[1,0]
	v_cvt_pk_bf16_f32 v19, v76, v77
	v_add_u32_e32 v76, 0x1000, v125
	s_waitcnt lgkmcnt(0)
	v_mfma_f32_16x16x32_bf16 v[42:45], v[68:71], v[54:57], v[42:45]
	v_mul_f32_e64 v32, v24, v84
	v_mul_f32_e64 v33, v25, v84
	v_add_u32_e32 v77, 0x1800, v125
	v_pk_mul_f32 v[40:41], v[40:41], v[108:109] op_sel_hi:[1,0]
	v_mfma_f32_16x16x32_bf16 v[68:71], v[68:71], v[26:29], v[46:49]
	v_mul_f32_e64 v38, v38, v108
	v_mul_f32_e64 v39, v39, v108
	v_pk_mul_f32 v[36:37], v[36:37], v[108:109] op_sel_hi:[1,0]
	v_pk_mul_f32 v[34:35], v[34:35], v[108:109] op_sel_hi:[1,0]
	ds_read2_b64 v[46:49], v76 offset0:64 offset1:68
	s_waitcnt lgkmcnt(0)
	v_mfma_f32_16x16x32_bf16 v[72:75], v[46:49], v[26:29], v[30:33]
	s_nop 2
	ds_read2_b64 v[30:33], v77 offset0:96 offset1:100
	v_pk_mul_f32 v[24:25], v[20:21], v[84:85] op_sel_hi:[1,0]
	v_cvt_pk_bf16_f32 v50, v132, v133
	v_mfma_f32_16x16x32_bf16 v[38:41], v[46:49], v[54:57], v[38:41]
	v_cvt_pk_bf16_f32 v51, v164, v165
	v_cvt_pk_bf16_f32 v52, v166, v167
	v_cvt_pk_bf16_f32 v53, v168, v169
	s_waitcnt lgkmcnt(0)
	v_mfma_f32_16x16x32_bf16 v[34:37], v[30:33], v[54:57], v[34:37]
	v_cvt_pk_bf16_f32 v18, v78, v79
	v_cvt_pk_bf16_f32 v20, v80, v81
	v_cvt_pk_bf16_f32 v21, v82, v83
	v_mfma_f32_16x16x32_bf16 v[54:57], v[30:33], v[26:29], v[22:25]
	s_mov_b64 s[0:1], 0x100
	v_add_u32_e32 v127, 64, v127
	v_lshl_add_u64 v[102:103], v[102:103], 0, s[0:1]
	ds_read2_b64 v[22:25], v125 offset0:8 offset1:12
	s_waitcnt lgkmcnt(0)
	v_mfma_f32_16x16x32_bf16 v[46:49], v[22:25], v[50:53], v[58:61]
	s_nop 2
	ds_read2_b64 v[58:61], v77 offset0:104 offset1:108
	v_add_u32_e32 v125, 0x4800, v125
	s_cmp_ge_i32 s9, s94
	v_mfma_f32_16x16x32_bf16 v[30:33], v[22:25], v[18:21], v[62:65]
	ds_read2_b64 v[22:25], v67 offset0:40 offset1:44
	v_mov_b32_e32 v109, v128
	s_waitcnt lgkmcnt(0)
	v_mfma_f32_16x16x32_bf16 v[42:45], v[22:25], v[50:53], v[42:45]
	v_mfma_f32_16x16x32_bf16 v[26:29], v[22:25], v[18:21], v[68:71]
	ds_read2_b64 v[22:25], v76 offset0:72 offset1:76
	s_waitcnt lgkmcnt(0)
	v_mfma_f32_16x16x32_bf16 v[38:41], v[22:25], v[50:53], v[38:41]
	v_mfma_f32_16x16x32_bf16 v[22:25], v[22:25], v[18:21], v[72:75]
	v_mfma_f32_16x16x32_bf16 v[34:37], v[58:61], v[50:53], v[34:37]
	v_mfma_f32_16x16x32_bf16 v[18:21], v[58:61], v[18:21], v[54:57]
	s_cbranch_scc0 .LBB0_276
	s_mov_b64 s[62:63], s[14:15]
	s_branch .LBB0_273
